# v58 + P5 queue order: attention units and conversion batches alternate (first 1024 pops) instead of all attention first
# speedup vs baseline: 1.0096x; 1.0077x over previous
; #define LAS __attribute__((address_space(3)))
; __device__ __forceinline__ void attn_wg(const bf16* PROJ, bf16* CONCAT, int wu, LAS unsigned char* L, int tid, int lane, int wave) {
;     const int half = wu & 1, bh = (wu >> 1) & 63, blk = 3 - (wu >> 7), h = bh & 15, b = bh >> 4;
;     const int rho = 4 * (wave & 3) + 2 * half + (wave >> 2);
;     const int i = lane & 31, hh = lane >> 5, l0 = blk * 32;
;     const int tq = 16 * (l0 + i) + rho;
;     const size_t rowbase = (size_t)b * SEQ;
;     bf16x8 qf[8];
;     f32x16 oacc[4];
; #pragma unroll
;     for (int dt = 0; dt < 4; ++dt)
; #pragma unroll
;         for (int r = 0; r < 16; ++r) oacc[dt][r] = 0.f;
;     float mrun = -1e30f, lrun = 0.f;
;     const int g16 = lane >> 4, i16 = lane & 15;
;     const int troff = (4 * (g16 >> 1) + (i16 >> 2)) * 320 + (16 * (g16 & 1) + 4 * (i16 & 3)) * 2;
;     const bf16* kbase = PROJ + rowbase * LDP + PJ_K + h * HD;
;     const bf16* vbase = PROJ + rowbase * LDP + PJ_V + h * HD;
;     constexpr int TILE = ATT_VS_BYTES;
;     __syncthreads();
;     { const int p = wave >> 1, odd = wave & 1;
;       const int tA = 512 * blk + 64 * wave + 4 * (i >> 1) + 2 * half + (i & 1);
;       { const bf16* qp = PROJ + (rowbase + tA) * LDP + PJ_Q + h * HD + 8 * hh;
; #pragma unroll
;         for (int s = 0; s < 8; ++s) qf[s] = *(const bf16x8*)(qp + 16 * s); }
; __global__ void __launch_bounds__(NWAVES * 64, 2) fwd(Args args) {
;     ...
;             const bool conv = DEFER_AT == 5 ? (q < 1024u ? (q & 1u) != 0u : true) : false; const int idx = DEFER_AT == 5 ? (q < 1024u ? (int)(q >> 1) : (int)(q - 512u)) : (int)q;
;     ...
;             const bool conv = q >= 512u; const int idx = conv ? (int)(q - 512u) : (int)q;
;     ...
;             const bool conv = q < (unsigned)NCB; const int idx = conv ? (int)q : (int)(q - (unsigned)NCB);
;     ...
;             if (!conv) attn_wg(PROJ, CONCAT, idx, L, tid, lane, wave);
.LBB0_646:
	s_or_b64 exec, exec, s[6:7]
	v_mbcnt_lo_u32_b32 v168, -1, 0
	v_mbcnt_hi_u32_b32 v168, -1, v168
	v_add_u32_e32 v185, s9, v168
	s_cmpk_gt_u32 s25, 0x3ff
	s_cbranch_scc1 .Lq5_conv
	s_and_b32 s4, s25, 1
	s_lshr_b32 s25, s25, 1
	s_cmp_eq_u32 s4, 0
	s_cbranch_scc1 .Lq5_attn
	s_addk_i32 s25, 0x200
.Lq5_conv:
	s_mov_b64 s[4:5], -1
	s_branch .LBB0_679
.Lq5_attn:
	s_lshl_b32 s4, s25, 1
	s_and_b32 s21, s4, 2
	s_lshl_b32 s4, s25, 6
	s_lshr_b32 s58, s25, 7
	s_and_b32 s64, s4, 0x1800
	s_sub_i32 s20, 3, s58
	s_mul_i32 s5, s64, 0x7080
	s_add_u32 s5, s34, s5
	s_addc_u32 s52, s35, 0
	s_and_b32 s42, s4, 0x780
	s_lshl_b32 s4, s20, 9
	v_lshlrev_b32_e32 v150, 1, v168
	s_add_i32 s6, s4, s9
	v_and_b32_e32 v3, 60, v150
	v_or_b32_e32 v0, s6, v3
	v_and_b32_e32 v4, 1, v168
	v_or3_b32 v0, v0, v4, s21
	s_mov_b32 s65, s43
	v_ashrrev_i32_e32 v1, 31, v0
	v_lshl_add_u64 v[0:1], v[0:1], 0, s[64:65]
	v_mov_b64_e32 v[6:7], s[34:35]
	v_ashrrev_i32_e32 v2, 5, v168
	v_mad_u64_u32 v[6:7], s[6:7], v0, s91, v[6:7]
	v_mad_i32_i24 v7, v1, s91, v7
	s_lshl_b32 s42, s42, 1
	v_lshlrev_b32_e32 v144, 3, v2
	v_lshl_add_u64 v[0:1], v[6:7], 0, s[42:43]
	v_ashrrev_i32_e32 v145, 31, v144
	v_lshl_add_u64 v[0:1], v[144:145], 1, v[0:1]
	s_barrier
	global_load_dwordx4 v[96:99], v[0:1], off
	global_load_dwordx4 v[100:103], v[0:1], off offset:32
	global_load_dwordx4 v[104:107], v[0:1], off offset:64
	global_load_dwordx4 v[108:111], v[0:1], off offset:96
	global_load_dwordx4 v[112:115], v[0:1], off offset:128
	global_load_dwordx4 v[116:119], v[0:1], off offset:160
	global_load_dwordx4 v[120:123], v[0:1], off offset:192
	global_load_dwordx4 v[124:127], v[0:1], off offset:224
	v_sub_u32_e32 v1, 0, v168
	v_max_i32_e32 v1, v168, v1
	v_mul_hi_u32 v5, v1, v163
	v_mul_lo_u32 v6, v5, s77
	v_sub_u32_e32 v1, v1, v6
	v_add_u32_e32 v6, 1, v5
	v_cmp_le_u32_e32 vcc, s77, v1
	v_ashrrev_i32_e32 v0, 31, v168
	s_add_u32 s5, s5, s42
	v_cndmask_b32_e32 v5, v5, v6, vcc
	v_subrev_u32_e32 v6, s77, v1
	v_cndmask_b32_e32 v1, v1, v6, vcc
	v_add_u32_e32 v6, 1, v5
	v_cmp_le_u32_e32 vcc, s77, v1
	s_addc_u32 s6, s52, 0
	s_add_u32 s60, s5, 0x1000
	v_cndmask_b32_e32 v1, v5, v6, vcc
	v_xor_b32_e32 v1, v1, v0
	v_sub_u32_e32 v0, v1, v0
	v_mul_lo_u32 v1, v0, s77
	v_sub_u32_e32 v1, v168, v1
	v_min_i32_e32 v0, 31, v0
	v_min_i32_e32 v1, 15, v1
	v_mul_lo_u32 v0, v0, s91
	v_lshl_add_u32 v160, v1, 4, v0
	v_add_u32_e32 v0, 64, v168
	v_sub_u32_e32 v5, 0, v0
	v_max_i32_e32 v5, v0, v5
	v_mul_hi_u32 v6, v5, v163
	v_mul_lo_u32 v7, v6, s77
	v_sub_u32_e32 v5, v5, v7
	v_add_u32_e32 v7, 1, v6
	v_cmp_le_u32_e32 vcc, s77, v5
	v_ashrrev_i32_e32 v1, 31, v0
	s_addc_u32 s61, s6, 0
	v_cndmask_b32_e32 v6, v6, v7, vcc
	v_subrev_u32_e32 v7, s77, v5
	v_cndmask_b32_e32 v5, v5, v7, vcc
	v_add_u32_e32 v7, 1, v6
	v_cmp_le_u32_e32 vcc, s77, v5
	s_add_u32 s62, s5, 0x2000
	s_addc_u32 s63, s6, 0
	v_cndmask_b32_e32 v5, v6, v7, vcc
	v_xor_b32_e32 v5, v5, v1
	v_sub_u32_e32 v1, v5, v1
	v_mul_lo_u32 v5, v1, s77
	v_sub_u32_e32 v0, v0, v5
	v_min_i32_e32 v1, 31, v1
	v_min_i32_e32 v0, 15, v0
	v_mul_lo_u32 v1, v1, s91
	v_lshl_add_u32 v128, v0, 4, v1
	v_add_u32_e32 v0, 0x80, v168
	v_sub_u32_e32 v5, 0, v0
	v_max_i32_e32 v5, v0, v5
	v_mul_hi_u32 v6, v5, v163
	v_mul_lo_u32 v7, v6, s77
	v_sub_u32_e32 v5, v5, v7
	v_add_u32_e32 v7, 1, v6
	v_cmp_le_u32_e32 vcc, s77, v5
	v_ashrrev_i32_e32 v1, 31, v0
	s_add_i32 s52, s78, s4
	v_cndmask_b32_e32 v6, v6, v7, vcc
	v_subrev_u32_e32 v7, s77, v5
	v_cndmask_b32_e32 v5, v5, v7, vcc
	v_add_u32_e32 v7, 1, v6
	v_cmp_le_u32_e32 vcc, s77, v5
	s_and_b64 s[4:5], s[48:49], exec
	s_cselect_b32 s53, s61, s63
	v_cndmask_b32_e32 v5, v6, v7, vcc
	v_xor_b32_e32 v5, v5, v1
	v_sub_u32_e32 v1, v5, v1
	v_mul_lo_u32 v5, v1, s77
	v_sub_u32_e32 v0, v0, v5
	v_min_i32_e32 v1, 31, v1
	v_min_i32_e32 v0, 15, v0
	v_mul_lo_u32 v1, v1, s91
	v_lshl_add_u32 v130, v0, 4, v1
	v_add_u32_e32 v0, 0xc0, v168
	v_sub_u32_e32 v5, 0, v0
	v_max_i32_e32 v5, v0, v5
	v_mul_hi_u32 v6, v5, v163
	v_mul_lo_u32 v7, v6, s77
	v_sub_u32_e32 v5, v5, v7
	v_add_u32_e32 v7, 1, v6
	v_cmp_le_u32_e32 vcc, s77, v5
	v_ashrrev_i32_e32 v1, 31, v0
	s_cselect_b32 s56, s60, s62
	v_cndmask_b32_e32 v6, v6, v7, vcc
	v_subrev_u32_e32 v7, s77, v5
	v_cndmask_b32_e32 v5, v5, v7, vcc
	v_add_u32_e32 v7, 1, v6
	v_cmp_le_u32_e32 vcc, s77, v5
	s_max_i32 s4, s52, 0
	s_mul_hi_u32 s5, s4, 0x7080
	v_cndmask_b32_e32 v5, v6, v7, vcc
	v_xor_b32_e32 v5, v5, v1
	v_sub_u32_e32 v1, v5, v1
	v_mul_lo_u32 v5, v1, s77
	v_sub_u32_e32 v0, v0, v5
	v_min_i32_e32 v1, 31, v1
	v_min_i32_e32 v0, 15, v0
	v_mul_lo_u32 v1, v1, s91
	v_lshl_add_u32 v132, v0, 4, v1
	v_add_u32_e32 v0, 0x100, v168
	v_sub_u32_e32 v5, 0, v0
	v_max_i32_e32 v5, v0, v5
	v_mul_hi_u32 v6, v5, v163
	v_mul_lo_u32 v7, v6, s77
	v_sub_u32_e32 v5, v5, v7
	v_add_u32_e32 v7, 1, v6
; #define LAS __attribute__((address_space(3)))
; __device__ __forceinline__ void attn_wg(const bf16* PROJ, bf16* CONCAT, int wu, LAS unsigned char* L, int tid, int lane, int wave) {
;     ...
;     { const int p = wave >> 1, odd = wave & 1;
;       const int tA = 512 * blk + 64 * wave + 4 * (i >> 1) + 2 * half + (i & 1);
;       { const bf16* qp = PROJ + (rowbase + tA) * LDP + PJ_Q + h * HD + 8 * hh;
; #pragma unroll
;         for (int s = 0; s < 8; ++s) qf[s] = *(const bf16x8*)(qp + 16 * s); }
;       unsigned doff[10];
; #pragma unroll
;       for (int n = 0; n < 10; ++n) { const int g = 64 * n + lane; const int per = odd ? 20 : 17; int row = g / per; int c = g - row * per; c = c < 15 ? c : 15; row = row < 31 ? row : 31;
;           doff[n] = (unsigned)(row * (LDP * 2) + c * 16); }
;       const int sp = 512 * blk + 128 * p - 128;
;       const char* gsrc = (const char*)(odd ? vbase : kbase);
;       LAS unsigned char* ldst = L + 2 * p * TILE + (odd ? ATT_KS_BYTES : 0);
;     ...
;       ATT_DMA(0);
;       asm volatile("s_waitcnt vmcnt(0)" ::: "memory");
	v_cmp_le_u32_e32 vcc, s77, v5
	v_ashrrev_i32_e32 v1, 31, v0
	s_mulk_i32 s4, 0x7080
	v_cndmask_b32_e32 v6, v6, v7, vcc
	v_subrev_u32_e32 v7, s77, v5
	v_cndmask_b32_e32 v5, v5, v7, vcc
	v_add_u32_e32 v7, 1, v6
	v_cmp_le_u32_e32 vcc, s77, v5
	s_add_u32 s66, s56, s4
	s_mov_b32 m0, s80
	v_cndmask_b32_e32 v5, v6, v7, vcc
	v_xor_b32_e32 v5, v5, v1
	v_sub_u32_e32 v1, v5, v1
	v_mul_lo_u32 v5, v1, s77
	v_sub_u32_e32 v0, v0, v5
	v_min_i32_e32 v1, 31, v1
	v_min_i32_e32 v0, 15, v0
	v_mul_lo_u32 v1, v1, s91
	v_lshl_add_u32 v134, v0, 4, v1
	v_add_u32_e32 v0, 0x140, v168
	v_sub_u32_e32 v5, 0, v0
	v_max_i32_e32 v5, v0, v5
	v_mul_hi_u32 v6, v5, v163
	v_mul_lo_u32 v7, v6, s77
	v_sub_u32_e32 v5, v5, v7
	v_add_u32_e32 v7, 1, v6
	v_cmp_le_u32_e32 vcc, s77, v5
	v_ashrrev_i32_e32 v1, 31, v0
	s_addc_u32 s67, s53, s5
	v_cndmask_b32_e32 v6, v6, v7, vcc
	v_subrev_u32_e32 v7, s77, v5
	v_cndmask_b32_e32 v5, v5, v7, vcc
	v_add_u32_e32 v7, 1, v6
	v_cmp_le_u32_e32 vcc, s77, v5
	global_load_lds_dwordx4 v160, s[66:67]
	s_nop 0
	v_cndmask_b32_e32 v5, v6, v7, vcc
	v_xor_b32_e32 v5, v5, v1
	v_sub_u32_e32 v1, v5, v1
	v_mul_lo_u32 v5, v1, s77
	v_sub_u32_e32 v0, v0, v5
	v_min_i32_e32 v1, 31, v1
	v_min_i32_e32 v0, 15, v0
	v_mul_lo_u32 v1, v1, s91
	v_lshl_add_u32 v136, v0, 4, v1
	v_add_u32_e32 v0, 0x180, v168
	v_sub_u32_e32 v5, 0, v0
	v_max_i32_e32 v5, v0, v5
	v_mul_hi_u32 v6, v5, v163
	v_mul_lo_u32 v7, v6, s77
	v_sub_u32_e32 v5, v5, v7
	v_add_u32_e32 v7, 1, v6
	v_cmp_le_u32_e32 vcc, s77, v5
	v_ashrrev_i32_e32 v1, 31, v0
	s_mov_b32 m0, s93
	v_cndmask_b32_e32 v6, v6, v7, vcc
	v_subrev_u32_e32 v7, s77, v5
	v_cndmask_b32_e32 v5, v5, v7, vcc
	v_add_u32_e32 v7, 1, v6
	v_cmp_le_u32_e32 vcc, s77, v5
	global_load_lds_dwordx4 v128, s[66:67]
	s_nop 0
	v_cndmask_b32_e32 v5, v6, v7, vcc
	v_xor_b32_e32 v5, v5, v1
	v_sub_u32_e32 v1, v5, v1
	v_mul_lo_u32 v5, v1, s77
	v_sub_u32_e32 v0, v0, v5
	v_min_i32_e32 v1, 31, v1
	v_min_i32_e32 v0, 15, v0
	v_mul_lo_u32 v1, v1, s91
	v_lshl_add_u32 v138, v0, 4, v1
	v_add_u32_e32 v0, 0x1c0, v168
	v_sub_u32_e32 v5, 0, v0
	v_max_i32_e32 v5, v0, v5
	v_mul_hi_u32 v6, v5, v163
	v_mul_lo_u32 v7, v6, s77
	v_sub_u32_e32 v5, v5, v7
	v_add_u32_e32 v7, 1, v6
	v_cmp_le_u32_e32 vcc, s77, v5
	v_ashrrev_i32_e32 v1, 31, v0
	s_mov_b32 m0, s94
	v_cndmask_b32_e32 v6, v6, v7, vcc
	v_subrev_u32_e32 v7, s77, v5
	v_cndmask_b32_e32 v5, v5, v7, vcc
	v_add_u32_e32 v7, 1, v6
	v_cmp_le_u32_e32 vcc, s77, v5
	global_load_lds_dwordx4 v130, s[66:67]
	s_nop 0
	v_cndmask_b32_e32 v5, v6, v7, vcc
	v_xor_b32_e32 v5, v5, v1
	v_sub_u32_e32 v1, v5, v1
	s_mov_b32 m0, s95
	v_mul_lo_u32 v5, v1, s77
	global_load_lds_dwordx4 v132, s[66:67]
	s_mov_b32 m0, s96
	v_sub_u32_e32 v0, v0, v5
	v_min_i32_e32 v1, 31, v1
	global_load_lds_dwordx4 v134, s[66:67]
	s_mov_b32 m0, s97
	v_min_i32_e32 v0, 15, v0
	v_mul_lo_u32 v1, v1, s91
	global_load_lds_dwordx4 v136, s[66:67]
	s_add_i32 m0, s80, 0x1800
	v_lshl_add_u32 v140, v0, 4, v1
	global_load_lds_dwordx4 v138, s[66:67]
	s_mov_b32 m0, s24
	v_add_u32_e32 v0, 0x200, v168
	global_load_lds_dwordx4 v140, s[66:67]
	v_sub_u32_e32 v5, 0, v0
	v_max_i32_e32 v5, v0, v5
	v_mul_hi_u32 v6, v5, v163
	v_mul_lo_u32 v7, v6, s77
	v_sub_u32_e32 v5, v5, v7
	v_add_u32_e32 v7, 1, v6
	v_cmp_le_u32_e32 vcc, s77, v5
	v_ashrrev_i32_e32 v1, 31, v0
	v_cmp_ne_u32_e64 s[4:5], 1, v166
	v_cndmask_b32_e32 v6, v6, v7, vcc
	v_subrev_u32_e32 v7, s77, v5
	v_cndmask_b32_e32 v5, v5, v7, vcc
	v_add_u32_e32 v7, 1, v6
	v_cmp_le_u32_e32 vcc, s77, v5
	s_nop 1
	v_cndmask_b32_e32 v5, v6, v7, vcc
	v_xor_b32_e32 v5, v5, v1
	v_sub_u32_e32 v1, v5, v1
	v_mul_lo_u32 v5, v1, s77
	v_sub_u32_e32 v0, v0, v5
	v_min_i32_e32 v1, 31, v1
	v_min_i32_e32 v0, 15, v0
	v_mul_lo_u32 v1, v1, s91
	s_waitcnt vmcnt(0)
	v_lshl_add_u32 v142, v0, 4, v1
	v_add_u32_e32 v0, 0x240, v168
	v_sub_u32_e32 v5, 0, v0
	v_max_i32_e32 v5, v0, v5
	v_mul_hi_u32 v6, v5, v163
	v_mul_lo_u32 v7, v6, s77
	v_sub_u32_e32 v5, v5, v7
	v_add_u32_e32 v7, 1, v6
	v_cmp_le_u32_e32 vcc, s77, v5
	v_ashrrev_i32_e32 v1, 31, v0
	s_nop 0
	v_cndmask_b32_e32 v6, v6, v7, vcc
	v_subrev_u32_e32 v7, s77, v5
	v_cndmask_b32_e32 v5, v5, v7, vcc
	v_add_u32_e32 v7, 1, v6
	v_cmp_le_u32_e32 vcc, s77, v5
	s_nop 1
	v_cndmask_b32_e32 v5, v6, v7, vcc
	v_xor_b32_e32 v5, v5, v1
	v_sub_u32_e32 v1, v5, v1
	v_mul_lo_u32 v5, v1, s77
	v_sub_u32_e32 v0, v0, v5
	v_min_i32_e32 v1, 31, v1
	v_min_i32_e32 v0, 15, v0
	v_mul_lo_u32 v1, v1, s91
	s_andn2_b64 vcc, exec, s[46:47]
	v_lshl_add_u32 v146, v0, 4, v1
	s_cbranch_vccnz .LBB0_649
	v_readlane_b32 s6, v240, 9
	s_mov_b32 m0, s6
	v_mov_b32_e32 v147, v161
	global_load_lds_dwordx4 v142, s[66:67]
	v_mov_b32_e32 v143, v161
	s_mov_b64 s[68:69], -1
	v_mov_b64_e32 v[0:1], v[146:147]
	s_movk_i32 s57, 0x2400
	v_cmp_gt_i32_e64 s[6:7], 32, v168
	s_cbranch_execz .LBB0_650
	s_branch .LBB0_651
